# pass 0 SSD state stores: sixteen 8-byte stores paired into eight 16-byte write-through stores (v_permlane16_swap)
# speedup vs baseline: 1.0109x; 1.0065x over previous
; #define LAS __attribute__((address_space(3)))
; __device__ __forceinline__ unsigned pk2(float lo, float hi) { const f32x2cv v = {lo, hi}; const bf16x2cv b = __builtin_convertvector(v, bf16x2cv); return __builtin_bit_cast(unsigned, b); }
; #define MFMA16(a, b, c) __builtin_amdgcn_mfma_f32_16x16x32_bf16((a), (b), (c), 0, 0, 0)
; template <int PASS>
; __device__ __forceinline__ void ssd_unit(LAS unsigned char* lds, int ch, int g, const bf16* PROJ, const bf16* XBC, const float* At, const float* DTt, bf16* STS, float* DECS, bf16* OMIX,
;                                          const float* d_skip, const float* ssd_norm) {
;     ...
;         __syncthreads();
;         {
;             const int hh = 4 * g + (wave & 3), d = wave >> 2; LAS unsigned char* XW = XT + (wave * 64) * RS; bf16* sp = STS + (size_t)((ch * 8 + hh) * 2 + d) * 4096;
; #pragma unroll
;             for (int nt = 0; nt < 4; ++nt) { const bf16x8 a0 = ldsfrag(BT, 16 * nt + lr, 0, lq), a1 = ldsfrag(BT, 16 * nt + lr, 1, lq);
; #pragma unroll
;                 for (int pt = 0; pt < 4; ++pt) { pg8::f32x4 acc = {0.f, 0.f, 0.f, 0.f};
;                     acc = MFMA16(a0, ldsfrag(XW, 16 * pt + lr, 0, lq), acc); acc = MFMA16(a1, ldsfrag(XW, 16 * pt + lr, 1, lq), acc);
;                     v2u o; o.x = pk2(acc[0], acc[1]); o.y = pk2(acc[2], acc[3]); *(v2u*)(sp + (16 * pt + lr) * 64 + 16 * nt + 4 * lq) = o; } }
;         }
.LBB0_603:
	s_or_b64 exec, exec, s[0:1]
	v_and_b32_e32 v70, 15, v4
	v_and_b32_e32 v2, 48, v4
	v_mul_u32_u24_e32 v5, 0x90, v70
	v_add3_u32 v82, 0, v5, v2
	s_waitcnt lgkmcnt(0)
	s_barrier
	v_mbcnt_lo_u32_b32 v122, -1, 0
	v_mbcnt_hi_u32_b32 v122, -1, v122
	v_bfe_u32 v122, v122, 4, 1
	v_mul_u32_u24_e32 v122, 24, v122
	v_mov_b32_e32 v123, 0
	ds_read_b128 v[6:9], v82 offset:18432
	s_mulk_i32 s26, 0x2400
	s_add_i32 s0, s26, 0
	v_add3_u32 v2, s0, v5, v2
	ds_read_b128 v[10:13], v82 offset:18496
	ds_read_b128 v[14:17], v2 offset:27648
	ds_read_b128 v[18:21], v2 offset:27712
	ds_read_b128 v[26:29], v2 offset:29952
	ds_read_b128 v[30:33], v2 offset:30016
	s_lshl_b32 s0, s12, 3
	s_or_b32 s0, s58, s0
	s_waitcnt lgkmcnt(3)
	v_mfma_f32_16x16x32_bf16 v[22:25], v[6:9], v[14:17], 0
	s_or_b32 s0, s0, s34
	ds_read_b128 v[38:41], v2 offset:32256
	ds_read_b128 v[42:45], v2 offset:32320
	ds_read_b128 v[50:53], v2 offset:34560
	ds_read_b128 v[54:57], v2 offset:34624
	s_waitcnt lgkmcnt(5)
	v_mfma_f32_16x16x32_bf16 v[34:37], v[6:9], v[26:29], 0
	s_lshl_b32 s0, s0, 1
	s_add_i32 s0, s0, s13
	s_ashr_i32 s1, s0, 31
	v_mfma_f32_16x16x32_bf16 v[22:25], v[10:13], v[18:21], v[22:25]
	s_lshl_b64 s[0:1], s[0:1], 13
	ds_read_b128 v[58:61], v82 offset:20736
	s_add_u32 s0, s28, s0
	s_waitcnt lgkmcnt(5)
	v_mfma_f32_16x16x32_bf16 v[34:37], v[10:13], v[30:33], v[34:37]
	v_lshrrev_b32_e32 v2, 1, v4
	s_addc_u32 s1, s29, s1
	v_and_b32_e32 v2, 24, v2
	s_waitcnt lgkmcnt(4)
	v_mfma_f32_16x16x32_bf16 v[46:49], v[6:9], v[38:41], 0
	v_lshl_add_u64 v[74:75], s[0:1], 0, v[2:3]
	v_lshlrev_b32_e32 v2, 7, v70
	v_cvt_pk_bf16_f32 v92, v22, v23
	s_waitcnt lgkmcnt(2)
	v_mfma_f32_16x16x32_bf16 v[6:9], v[6:9], v[50:53], 0
	v_cvt_pk_bf16_f32 v93, v24, v25
	v_lshl_add_u64 v[76:77], v[74:75], 0, v[2:3]
	v_mfma_f32_16x16x32_bf16 v[46:49], v[10:13], v[42:45], v[46:49]
	v_cvt_pk_bf16_f32 v100, v34, v35
	v_cvt_pk_bf16_f32 v101, v36, v37
	ds_read_b128 v[34:37], v82 offset:23040
	ds_read_b128 v[70:73], v82 offset:23104
	s_waitcnt lgkmcnt(3)
	v_mfma_f32_16x16x32_bf16 v[6:9], v[10:13], v[54:57], v[6:9]
	ds_read_b128 v[10:13], v82 offset:20800
	v_or_b32_e32 v78, 0x800, v2
	v_mov_b32_e32 v79, v3
	s_waitcnt lgkmcnt(3)
	v_mfma_f32_16x16x32_bf16 v[62:65], v[58:61], v[14:17], 0
	v_lshl_add_u64 v[78:79], v[74:75], 0, v[78:79]
	v_or_b32_e32 v80, 0x1000, v2
	v_mov_b32_e32 v81, v3
	v_mfma_f32_16x16x32_bf16 v[66:69], v[58:61], v[26:29], 0
	v_cvt_pk_bf16_f32 v108, v46, v47
	v_cvt_pk_bf16_f32 v109, v48, v49
	v_mfma_f32_16x16x32_bf16 v[22:25], v[58:61], v[38:41], 0
	v_lshl_add_u64 v[80:81], v[74:75], 0, v[80:81]
	v_or_b32_e32 v2, 0x1800, v2
	v_mfma_f32_16x16x32_bf16 v[58:61], v[58:61], v[50:53], 0
	v_lshl_add_u64 v[74:75], v[74:75], 0, v[2:3]
	s_mov_b64 s[0:1], 0
	s_waitcnt lgkmcnt(0)
	v_mfma_f32_16x16x32_bf16 v[62:65], v[10:13], v[18:21], v[62:65]
	v_mfma_f32_16x16x32_bf16 v[66:69], v[10:13], v[30:33], v[66:69]
	v_mfma_f32_16x16x32_bf16 v[22:25], v[10:13], v[42:45], v[22:25]
	v_mfma_f32_16x16x32_bf16 v[10:13], v[10:13], v[54:57], v[58:61]
	v_mfma_f32_16x16x32_bf16 v[58:61], v[34:37], v[14:17], 0
	v_mfma_f32_16x16x32_bf16 v[46:49], v[70:73], v[18:21], v[58:61]
	s_nop 6
	v_cvt_pk_bf16_f32 v84, v6, v7
	v_mfma_f32_16x16x32_bf16 v[4:7], v[34:37], v[26:29], 0
	v_cvt_pk_bf16_f32 v85, v8, v9
	v_cvt_pk_bf16_f32 v94, v62, v63
	v_cvt_pk_bf16_f32 v95, v64, v65
	ds_read_b128 v[62:65], v82 offset:25344
	s_nop 1
	v_permlane16_swap_b32 v92, v94
	v_permlane16_swap_b32 v93, v95
	v_lshl_add_u64 v[120:121], v[76:77], 0, v[122:123]
	global_store_dwordx4 v[120:121], v[92:95], off sc1
	v_cvt_pk_bf16_f32 v102, v66, v67
	v_cvt_pk_bf16_f32 v103, v68, v69
	v_mfma_f32_16x16x32_bf16 v[4:7], v[70:73], v[30:33], v[4:7]
	s_nop 1
	v_permlane16_swap_b32 v100, v102
	v_permlane16_swap_b32 v101, v103
	v_lshl_add_u64 v[120:121], v[78:79], 0, v[122:123]
	global_store_dwordx4 v[120:121], v[100:103], off sc1
	v_cvt_pk_bf16_f32 v110, v22, v23
	v_cvt_pk_bf16_f32 v111, v24, v25
	ds_read_b128 v[22:25], v82 offset:25408
	v_mfma_f32_16x16x32_bf16 v[58:61], v[34:37], v[38:41], 0
	s_nop 1
	v_cvt_pk_bf16_f32 v104, v4, v5
	v_cvt_pk_bf16_f32 v105, v6, v7
	v_mfma_f32_16x16x32_bf16 v[34:37], v[34:37], v[50:53], 0
	s_nop 1
	v_permlane16_swap_b32 v108, v110
	v_permlane16_swap_b32 v109, v111
	v_lshl_add_u64 v[120:121], v[80:81], 0, v[122:123]
	global_store_dwordx4 v[120:121], v[108:111], off sc1
	v_cvt_pk_bf16_f32 v86, v10, v11
	v_cvt_pk_bf16_f32 v87, v12, v13
	s_waitcnt lgkmcnt(1)
	v_mfma_f32_16x16x32_bf16 v[4:7], v[62:65], v[26:29], 0
	s_nop 1
	v_permlane16_swap_b32 v84, v86
	v_permlane16_swap_b32 v85, v87
	v_lshl_add_u64 v[120:121], v[74:75], 0, v[122:123]
	global_store_dwordx4 v[120:121], v[84:87], off sc1
	v_cvt_pk_bf16_f32 v96, v46, v47
	v_cvt_pk_bf16_f32 v97, v48, v49
	v_mfma_f32_16x16x32_bf16 v[58:61], v[70:73], v[42:45], v[58:61]
	v_mfma_f32_16x16x32_bf16 v[34:37], v[70:73], v[54:57], v[34:37]
	v_mfma_f32_16x16x32_bf16 v[8:11], v[62:65], v[14:17], 0
	s_nop 4
	v_cvt_pk_bf16_f32 v112, v58, v59
	v_cvt_pk_bf16_f32 v113, v60, v61
	s_waitcnt lgkmcnt(0)
	v_mfma_f32_16x16x32_bf16 v[4:7], v[22:25], v[30:33], v[4:7]
	v_cvt_pk_bf16_f32 v88, v34, v35
	v_cvt_pk_bf16_f32 v89, v36, v37
	v_mfma_f32_16x16x32_bf16 v[8:11], v[22:25], v[18:21], v[8:11]
	v_mfma_f32_16x16x32_bf16 v[12:15], v[62:65], v[38:41], 0
	s_nop 2
	v_cvt_pk_bf16_f32 v106, v4, v5
	v_cvt_pk_bf16_f32 v107, v6, v7
	s_nop 1
	v_permlane16_swap_b32 v104, v106
	v_permlane16_swap_b32 v105, v107
	v_lshl_add_u64 v[120:121], v[78:79], 0, v[122:123]
	global_store_dwordx4 v[120:121], v[104:107], off offset:64 sc1
	v_mfma_f32_16x16x32_bf16 v[4:7], v[62:65], v[50:53], 0
	v_cvt_pk_bf16_f32 v98, v8, v9
	v_cvt_pk_bf16_f32 v99, v10, v11
	s_nop 1
	v_permlane16_swap_b32 v96, v98
	v_permlane16_swap_b32 v97, v99
	v_lshl_add_u64 v[120:121], v[76:77], 0, v[122:123]
	global_store_dwordx4 v[120:121], v[96:99], off offset:64 sc1
	v_mfma_f32_16x16x32_bf16 v[8:11], v[22:25], v[42:45], v[12:15]
	v_mfma_f32_16x16x32_bf16 v[4:7], v[22:25], v[54:57], v[4:7]
	s_nop 6
	v_cvt_pk_bf16_f32 v114, v8, v9
	v_cvt_pk_bf16_f32 v115, v10, v11
	v_cvt_pk_bf16_f32 v90, v4, v5
	v_cvt_pk_bf16_f32 v91, v6, v7
	s_nop 1
	v_permlane16_swap_b32 v112, v114
	v_permlane16_swap_b32 v113, v115
	v_lshl_add_u64 v[120:121], v[80:81], 0, v[122:123]
	global_store_dwordx4 v[120:121], v[112:115], off offset:64 sc1
	s_nop 1
	v_permlane16_swap_b32 v88, v90
	v_permlane16_swap_b32 v89, v91
	v_lshl_add_u64 v[120:121], v[74:75], 0, v[122:123]
	global_store_dwordx4 v[120:121], v[88:91], off offset:64 sc1
	s_barrier
